# diff_attn unit prologue: Q-fragment loads no longer drained before the first K/V tile DMAs (covered by the counted vmcnt(8))
# speedup vs baseline: 1.0029x; 1.0001x over previous
.LBB0_1614:
	s_lshl_b32 s5, s49, 1
	s_add_i32 s10, s5, 2
	v_mov_b32_e32 v36, v154
	s_and_b64 s[72:73], s[0:1], exec
	s_cselect_b32 s47, s10, 17
	v_ashrrev_i32_e32 v28, 6, v36
	s_or_b32 s5, s5, 1
	v_lshlrev_b32_e32 v2, 4, v28
	s_and_b64 s[72:73], s[0:1], exec
	v_and_b32_e32 v3, 48, v2
	s_cselect_b32 s5, s5, 17
	v_and_b32_e32 v0, 15, v36
	s_ashr_i32 s49, s48, 31
	v_cndmask_b32_e64 v2, v3, v2, s[0:1]
	v_ashrrev_i32_e32 v3, 31, v2
	v_lshl_add_u64 v[4:5], v[0:1], 0, s[48:49]
	v_lshl_add_u64 v[2:3], v[4:5], 0, v[2:3]
	s_and_b64 s[0:1], s[0:1], exec
	v_lshlrev_b64 v[110:111], 11, v[2:3]
	v_bfe_u32 v145, v36, 4, 2
	s_cselect_b32 s0, s10, 0
	v_lshl_add_u64 v[2:3], s[28:29], 0, v[110:111]
	s_ashr_i32 s77, s76, 31
	v_lshl_add_u64 v[2:3], s[76:77], 1, v[2:3]
	v_lshlrev_b32_e32 v108, 4, v145
	v_mov_b32_e32 v109, v1
	v_lshl_add_u64 v[2:3], v[2:3], 0, v[108:109]
	global_load_dwordx4 v[4:7], v[2:3], off
	global_load_dwordx4 v[8:11], v[2:3], off offset:64
	global_load_dwordx4 v[12:15], v[2:3], off offset:128
	global_load_dwordx4 v[16:19], v[2:3], off offset:192
	v_mov_b64_e32 v[2:3], s[50:51]
	v_ashrrev_i32_e32 v20, 4, v36
	v_ashrrev_i32_e32 v22, 3, v36
	v_readfirstlane_b32 s10, v36
	v_mad_i64_i32 v[24:25], s[50:51], s46, v22, 0
	v_xor_b32_e32 v22, v22, v36
	v_mad_i64_i32 v[2:3], s[50:51], v20, s53, v[2:3]
	v_xor_b32_e32 v26, v20, v36
	v_lshlrev_b32_e32 v22, 4, v22
	v_mov_b32_e32 v29, s5
	s_lshl_b32 s5, s10, 4
	s_add_i32 s50, s47, -1
	v_mov_b32_e32 v23, v1
	v_lshlrev_b32_e32 v20, 4, v26
	v_lshl_add_u64 v[24:25], v[24:25], 1, s[6:7]
	v_and_b32_e32 v22, 0x70, v22
	s_and_b32 s51, s5, 0xfffffc00
	s_min_u32 s5, s50, 2
	v_mov_b32_e32 v21, v1
	s_mov_b32 s49, s11
	v_and_b32_e32 v20, 0xf0, v20
	v_lshl_add_u64 v[114:115], v[24:25], 0, v[22:23]
	s_lshl_b32 s48, s5, 7
	v_lshl_add_u64 v[112:113], v[2:3], 0, v[20:21]
	s_add_i32 s51, s51, 0
	v_lshl_add_u64 v[32:33], v[114:115], 0, s[48:49]
	v_lshl_add_u64 v[2:3], v[112:113], 0, s[78:79]
	v_mov_b32_e32 v30, s0
	s_mul_i32 s0, s5, 0x18000
	s_add_i32 s5, s51, 0x2000
	s_lshl_b32 s10, s46, 7
	s_add_i32 s6, s51, 0x4000
	v_lshl_add_u64 v[26:27], v[114:115], 0, s[10:11]
	s_add_i32 s7, s51, 0x6000
	v_lshl_add_u64 v[20:21], v[112:113], 0, s[20:21]
	s_add_i32 s47, s51, 0x8000
	v_lshl_add_u64 v[24:25], v[112:113], 0, s[82:83]
	s_add_i32 s72, s51, 0xa000
	v_lshl_add_u64 v[22:23], v[114:115], 0, s[80:81]
	v_cmp_gt_i32_e32 vcc, 4, v28
	s_add_i32 s73, s51, 0xc000
	s_mov_b32 s1, s11
	v_cndmask_b32_e32 v109, v30, v29, vcc
	v_lshl_add_u64 v[28:29], v[26:27], 0, s[80:81]
	s_add_i32 s74, s51, 0xe000
	v_lshl_add_u64 v[30:31], v[112:113], 0, s[0:1]
	s_add_i32 s0, s51, 0x10000
	s_add_i32 s1, s51, 0x12000
	v_lshl_add_u64 v[34:35], v[30:31], 0, s[78:79]
	s_add_i32 s48, s51, 0x14000
	v_xor_b32_e32 v95, v145, v0
	v_bitop3_b32 v94, v145, v0, 4 bitop3:0x36
	v_lshlrev_b32_e32 v152, 8, v0
	v_lshlrev_b32_e32 v153, 7, v0
	v_lshlrev_b32_e32 v155, 4, v95
	v_lshlrev_b32_e32 v156, 4, v94
	s_waitcnt lgkmcnt(0)
	s_waitcnt lgkmcnt(0)
	s_barrier
	s_mov_b32 s49, m0
	s_mov_b32 m0, s51
	s_nop 0
	global_load_lds_dwordx4 v[112:113], off
	s_mov_b32 m0, s49
	s_nop 0
	s_mov_b32 s49, m0
	s_mov_b32 m0, s5
	s_nop 0
	global_load_lds_dwordx4 v[2:3], off
	s_mov_b32 m0, s49
	s_mov_b32 s5, m0
	s_mov_b32 m0, s6
	s_nop 0
	global_load_lds_dwordx4 v[114:115], off
	s_mov_b32 m0, s5
	v_lshl_add_u64 v[2:3], v[32:33], 0, s[10:11]
	s_mov_b32 s5, m0
	s_mov_b32 m0, s7
	s_nop 0
	global_load_lds_dwordx4 v[26:27], off
	s_mov_b32 m0, s5
	s_nop 0
	s_mov_b32 s5, m0
	s_mov_b32 m0, s47
	s_nop 0
	global_load_lds_dwordx4 v[20:21], off
	s_mov_b32 m0, s5
	s_nop 0
	s_mov_b32 s5, m0
	s_mov_b32 m0, s72
	s_nop 0
	global_load_lds_dwordx4 v[24:25], off
	s_mov_b32 m0, s5
	s_nop 0
	s_mov_b32 s5, m0
	s_mov_b32 m0, s73
	s_nop 0
	global_load_lds_dwordx4 v[22:23], off
	s_mov_b32 m0, s5
	v_and_b32_e32 v22, 7, v36
	s_mov_b32 s5, m0
	s_mov_b32 m0, s74
	s_nop 0
	global_load_lds_dwordx4 v[28:29], off
	s_mov_b32 m0, s5
	v_xor_b32_e32 v93, v145, v22
	s_mov_b32 s5, m0
	s_mov_b32 m0, s0
	s_nop 0
	global_load_lds_dwordx4 v[30:31], off
	s_mov_b32 m0, s5
	s_mov_b32 s0, m0
	s_mov_b32 m0, s1
	s_nop 0
	global_load_lds_dwordx4 v[34:35], off
	s_mov_b32 m0, s0
	s_min_u32 s5, s50, 3
	s_mov_b32 s0, m0
	s_mov_b32 m0, s48
	s_nop 0
	global_load_lds_dwordx4 v[32:33], off
	s_mov_b32 m0, s0
	s_add_i32 s0, s51, 0x16000
	s_mov_b32 s1, m0
	s_mov_b32 m0, s0
	s_nop 0
	global_load_lds_dwordx4 v[2:3], off
	s_mov_b32 m0, s1
	s_mul_i32 s0, s5, 0x18000
	s_mov_b32 s1, s11
	v_lshl_add_u64 v[2:3], v[112:113], 0, s[0:1]
	s_lshl_b32 s0, s5, 7
	s_waitcnt vmcnt(8)
	s_barrier
	v_lshl_add_u64 v[20:21], v[114:115], 0, s[0:1]
	s_add_i32 s0, s51, 0x18000
	s_mov_b32 s1, m0
	s_mov_b32 m0, s0
	s_nop 0
	global_load_lds_dwordx4 v[2:3], off
	s_mov_b32 m0, s1
	v_lshl_add_u64 v[2:3], v[2:3], 0, s[78:79]
	s_add_i32 s0, s51, 0x1a000
	s_mov_b32 s1, m0
	s_mov_b32 m0, s0
	s_nop 0
	global_load_lds_dwordx4 v[2:3], off
	s_mov_b32 m0, s1
	s_add_i32 s0, s51, 0x1c000
	s_mov_b32 s1, m0
	s_mov_b32 m0, s0
	s_nop 0
	global_load_lds_dwordx4 v[20:21], off
	s_mov_b32 m0, s1
	v_lshl_add_u64 v[2:3], v[20:21], 0, s[10:11]
	s_add_i32 s0, s51, 0x1e000
	s_mov_b32 s1, m0
	s_mov_b32 m0, s0
	s_nop 0
	global_load_lds_dwordx4 v[2:3], off
	s_mov_b32 m0, s1
	v_bitop3_b32 v3, v145, v0, 8 bitop3:0x36
	v_bitop3_b32 v2, v145, v0, 12 bitop3:0x36
	v_bitop3_b32 v92, v145, v22, 4 bitop3:0x36
	v_cmp_ne_u32_e64 s[0:1], 0, v109
	v_lshlrev_b32_e32 v157, 4, v3
	v_lshlrev_b32_e32 v158, 4, v2
	v_lshlrev_b32_e32 v159, 4, v93
	v_lshlrev_b32_e32 v160, 4, v92
	s_and_saveexec_b64 s[6:7], s[0:1]
	s_xor_b64 s[48:49], exec, s[6:7]
	s_cbranch_execz .LBB0_1616
	v_add_u32_e32 v0, 0, v152
	v_lshlrev_b32_e32 v155, 4, v95
	v_lshlrev_b32_e32 v156, 4, v94
	v_add_u32_e32 v36, v0, v155
	v_add_u32_e32 v40, v0, v156
	ds_read_b128 v[20:23], v36
	ds_read_b128 v[24:27], v36 offset:4096
	ds_read_b128 v[28:31], v40
	s_waitcnt lgkmcnt(2)
	v_mfma_f32_16x16x32_bf16 v[20:23], v[20:23], v[4:7], 0
	ds_read_b128 v[32:35], v40 offset:4096
	v_lshlrev_b32_e32 v157, 4, v3
	v_add_u32_e32 v3, v0, v157
	s_waitcnt lgkmcnt(1)
	v_mfma_f32_16x16x32_bf16 v[20:23], v[28:31], v[8:11], v[20:23]
	ds_read_b128 v[28:31], v36 offset:8192
	v_lshlrev_b32_e32 v158, 4, v2
	v_add_u32_e32 v2, v0, v158
	v_mfma_f32_16x16x32_bf16 v[24:27], v[24:27], v[4:7], 0
	s_nop 3
	v_mul_f32_e32 v68, 0x3e38aa3b, v22
	v_mul_f32_e32 v69, 0x3e38aa3b, v23
	v_sub_u32_e32 v0, v0, v153
	s_waitcnt lgkmcnt(0)
	v_mfma_f32_16x16x32_bf16 v[28:31], v[28:31], v[4:7], 0
	v_lshlrev_b32_e32 v159, 4, v93
	s_mov_b32 s6, s4
	s_mov_b32 s7, s4
	v_mfma_f32_16x16x32_bf16 v[24:27], v[32:35], v[8:11], v[24:27]
	ds_read_b128 v[32:35], v40 offset:8192
	ds_read_b128 v[36:39], v36 offset:12288
	ds_read_b128 v[40:43], v40 offset:12288
	s_mov_b32 s5, s4
	v_mov_b64_e32 v[126:127], s[6:7]
	s_waitcnt lgkmcnt(2)
	v_mfma_f32_16x16x32_bf16 v[28:31], v[32:35], v[8:11], v[28:31]
	ds_read_b128 v[32:35], v3
	ds_read_b128 v[44:47], v3 offset:4096
	ds_read_b128 v[48:51], v2
	ds_read_b128 v[52:55], v2 offset:4096
	ds_read_b128 v[56:59], v3 offset:8192
	ds_read_b128 v[60:63], v3 offset:12288
	v_mul_f32_e32 v3, 0x3e38aa3b, v21
	s_waitcnt lgkmcnt(7)
	v_mfma_f32_16x16x32_bf16 v[36:39], v[36:39], v[4:7], 0
	v_mul_f32_e32 v72, 0x3e38aa3b, v26
	v_mul_f32_e32 v73, 0x3e38aa3b, v27
	v_mul_f32_e32 v70, 0x3e38aa3b, v24
	s_waitcnt lgkmcnt(5)
	v_mfma_f32_16x16x32_bf16 v[32:35], v[32:35], v[12:15], 0
	v_mul_f32_e32 v71, 0x3e38aa3b, v25
	v_mul_f32_e32 v74, 0x3e38aa3b, v28
	v_mul_f32_e32 v75, 0x3e38aa3b, v29
	v_mfma_f32_16x16x32_bf16 v[36:39], v[40:43], v[8:11], v[36:39]
	ds_read_b128 v[40:43], v2 offset:8192
	ds_read_b128 v[64:67], v2 offset:12288
	v_mul_f32_e32 v2, 0x3e38aa3b, v20
	v_mov_b64_e32 v[124:125], s[4:5]
	s_waitcnt lgkmcnt(5)
	v_mfma_f32_16x16x32_bf16 v[32:35], v[48:51], v[16:19], v[32:35]
	v_lshlrev_b32_e32 v160, 4, v92
	s_waitcnt lgkmcnt(3)
	v_mfma_f32_16x16x32_bf16 v[48:51], v[56:59], v[12:15], 0
	v_mul_f32_e32 v56, 0x3e38aa3b, v38
	v_mul_f32_e32 v57, 0x3e38aa3b, v39
	v_mfma_f32_16x16x32_bf16 v[44:47], v[44:47], v[12:15], 0
	s_waitcnt lgkmcnt(1)
	v_mfma_f32_16x16x32_bf16 v[40:43], v[40:43], v[16:19], v[48:51]
	s_nop 2
	v_max_f32_e32 v48, v68, v69
	v_max3_f32 v2, v2, v3, v48
	v_max_f32_e32 v3, v72, v73
	v_mfma_f32_16x16x32_bf16 v[44:47], v[52:55], v[16:19], v[44:47]
	v_mul_f32_e32 v52, 0x3e38aa3b, v30
	v_mul_f32_e32 v53, 0x3e38aa3b, v31
	v_max3_f32 v3, v70, v71, v3
	v_mul_f32_e32 v54, 0x3e38aa3b, v36
	v_mul_f32_e32 v55, 0x3e38aa3b, v37
	v_max3_f32 v2, v2, s25, v3
	v_max_f32_e32 v3, v52, v53
	v_max_f32_e32 v48, v56, v57
	v_max3_f32 v3, v74, v75, v3
	v_max3_f32 v48, v54, v55, v48
	v_max3_f32 v2, v2, v3, v48
	ds_bpermute_b32 v3, v146, v2
	v_mfma_f32_16x16x32_bf16 v[48:51], v[60:63], v[12:15], 0
	v_mul_f32_e32 v53, 0x3e38aa3b, v34
	v_mul_f32_e32 v54, 0x3e38aa3b, v35
	v_mul_f32_e32 v52, 0x3e38aa3b, v33
	s_waitcnt lgkmcnt(0)
	v_max_f32_e32 v3, v3, v3
	v_max_f32_e32 v2, v2, v3
	ds_bpermute_b32 v3, v147, v2
	v_mfma_f32_16x16x32_bf16 v[48:51], v[64:67], v[16:19], v[48:51]
	v_mul_f32_e32 v57, 0x3e38aa3b, v46
	v_mul_f32_e32 v58, 0x3e38aa3b, v47
	v_max_f32_e32 v53, v53, v54
	s_waitcnt lgkmcnt(0)
	v_max_f32_e32 v3, v3, v3
	v_max_f32_e32 v3, v2, v3
	v_fma_f32 v2, v27, s24, -v3
	v_mul_f32_e32 v27, 0x3e38aa3b, v32
	v_mul_f32_e32 v55, 0x3e38aa3b, v44
	v_mul_f32_e32 v56, 0x3e38aa3b, v45
	v_max3_f32 v27, v27, v52, v53
	v_max_f32_e32 v52, v57, v58
	v_mul_f32_e32 v61, 0x3e38aa3b, v42
	v_mul_f32_e32 v62, 0x3e38aa3b, v43
	v_mul_f32_e32 v65, 0x3e38aa3b, v50
	v_mul_f32_e32 v66, 0x3e38aa3b, v51
	v_max3_f32 v52, v55, v56, v52
	v_mul_f32_e32 v59, 0x3e38aa3b, v40
	v_mul_f32_e32 v60, 0x3e38aa3b, v41
	v_mul_f32_e32 v63, 0x3e38aa3b, v48
	v_mul_f32_e32 v64, 0x3e38aa3b, v49
	v_max3_f32 v27, v27, s25, v52
	v_max_f32_e32 v52, v61, v62
	v_max_f32_e32 v53, v65, v66
	v_max3_f32 v52, v59, v60, v52
	v_max3_f32 v53, v63, v64, v53
	v_max3_f32 v27, v27, v52, v53
	ds_bpermute_b32 v52, v146, v27
	v_fma_f32 v20, v20, s24, -v3
	v_exp_f32_e32 v53, v20
	v_fma_f32 v21, v21, s24, -v3
	v_exp_f32_e32 v54, v21
	s_waitcnt lgkmcnt(0)
	v_max_f32_e32 v20, v52, v52
	v_max_f32_e32 v20, v27, v20
	ds_bpermute_b32 v21, v147, v20
	v_exp_f32_e32 v58, v2
	v_fma_f32 v24, v24, s24, -v3
	v_fma_f32 v25, v25, s24, -v3
	v_fma_f32 v26, v26, s24, -v3
	s_waitcnt lgkmcnt(0)
	v_max_f32_e32 v2, v21, v21
	v_fma_f32 v23, v23, s24, -v3
	v_fma_f32 v22, v22, s24, -v3
	v_max_f32_e32 v2, v20, v2
	v_exp_f32_e32 v55, v22
	v_exp_f32_e32 v56, v23
	v_exp_f32_e32 v27, v24
	v_exp_f32_e32 v52, v25
	v_exp_f32_e32 v57, v26
	v_fma_f32 v24, v47, s24, -v2
	v_fma_f32 v20, v44, s24, -v2
	v_fma_f32 v21, v45, s24, -v2
	v_fma_f32 v25, v46, s24, -v2
	v_fma_f32 v22, v35, s24, -v2
	v_fma_f32 v23, v32, s24, -v2
	v_fma_f32 v26, v33, s24, -v2
	v_fma_f32 v32, v34, s24, -v2
	v_exp_f32_e32 v33, v23
	v_exp_f32_e32 v34, v26
	v_exp_f32_e32 v35, v32
	v_exp_f32_e32 v59, v22
	v_exp_f32_e32 v60, v20
	v_exp_f32_e32 v61, v21
	v_exp_f32_e32 v62, v25
	v_exp_f32_e32 v63, v24
	v_add_u32_e32 v68, v0, v159
	v_cvt_pk_bf16_f32 v32, v33, v34
	v_cvt_pk_bf16_f32 v33, v35, v59
	v_cvt_pk_bf16_f32 v34, v60, v61
	v_cvt_pk_bf16_f32 v35, v62, v63
	ds_read_b128 v[60:63], v68 offset:20480
	ds_read_b128 v[64:67], v68 offset:22528
	v_cvt_pk_bf16_f32 v24, v53, v54
	v_cvt_pk_bf16_f32 v25, v55, v56
	v_cvt_pk_bf16_f32 v26, v27, v52
	v_cvt_pk_bf16_f32 v27, v57, v58
	v_fma_f32 v69, v39, s24, -v3
	v_fma_f32 v70, v36, s24, -v3
	s_waitcnt lgkmcnt(1)
	v_mfma_f32_16x16x32_bf16 v[76:79], v[60:63], v[24:27], 0
	v_fma_f32 v71, v37, s24, -v3
	v_fma_f32 v72, v38, s24, -v3
	v_fma_f32 v28, v28, s24, -v3
	v_mfma_f32_16x16x32_bf16 v[36:39], v[60:63], v[32:35], 0
	ds_read_b128 v[60:63], v68 offset:24576
	v_fma_f32 v29, v29, s24, -v3
	ds_read_b128 v[20:23], v68 offset:16384
	ds_read_b128 v[44:47], v68 offset:18432
	v_fma_f32 v73, v31, s24, -v3
	s_waitcnt lgkmcnt(3)
	v_mfma_f32_16x16x32_bf16 v[80:83], v[64:67], v[24:27], 0
	v_fma_f32 v74, v30, s24, -v3
	v_exp_f32_e32 v75, v28
	v_exp_f32_e32 v93, v29
	v_mfma_f32_16x16x32_bf16 v[28:31], v[64:67], v[32:35], 0
	ds_read_b128 v[64:67], v68 offset:26624
	v_fma_f32 v106, v51, s24, -v2
	v_fma_f32 v107, v48, s24, -v2
	s_waitcnt lgkmcnt(3)
	v_mfma_f32_16x16x32_bf16 v[84:87], v[60:63], v[24:27], 0
	v_fma_f32 v132, v49, s24, -v2
	v_fma_f32 v133, v50, s24, -v2
	ds_read_b128 v[48:51], v68 offset:30720
	v_mfma_f32_16x16x32_bf16 v[88:91], v[60:63], v[32:35], 0
	ds_read_b128 v[60:63], v68 offset:28672
	v_add_u32_e32 v0, v0, v160
	v_fma_f32 v43, v43, s24, -v2
	s_waitcnt lgkmcnt(4)
	v_mfma_f32_16x16x32_bf16 v[52:55], v[20:23], v[24:27], 0
	v_fma_f32 v40, v40, s24, -v2
	v_fma_f32 v41, v41, s24, -v2
	v_fma_f32 v42, v42, s24, -v2
	s_waitcnt lgkmcnt(3)
	v_mfma_f32_16x16x32_bf16 v[56:59], v[44:47], v[24:27], 0
	v_exp_f32_e32 v74, v74
	v_exp_f32_e32 v73, v73
	v_exp_f32_e32 v70, v70
	s_waitcnt lgkmcnt(2)
	v_mfma_f32_16x16x32_bf16 v[94:97], v[64:67], v[24:27], 0
	v_exp_f32_e32 v71, v71
	v_exp_f32_e32 v72, v72
	v_exp_f32_e32 v69, v69
	s_waitcnt lgkmcnt(0)
	v_mfma_f32_16x16x32_bf16 v[102:105], v[60:63], v[24:27], 0
	v_exp_f32_e32 v40, v40
	v_exp_f32_e32 v41, v41
	v_exp_f32_e32 v42, v42
	v_mfma_f32_16x16x32_bf16 v[120:123], v[48:51], v[24:27], 0
	v_exp_f32_e32 v43, v43
	v_cvt_pk_bf16_f32 v162, v75, v93
	v_cvt_pk_bf16_f32 v163, v74, v73
	v_mfma_f32_16x16x32_bf16 v[128:131], v[48:51], v[32:35], 0
	v_exp_f32_e32 v49, v132
	v_exp_f32_e32 v50, v133
	v_exp_f32_e32 v48, v107
	v_mfma_f32_16x16x32_bf16 v[132:135], v[124:127], v[24:27], 0
	ds_read_b128 v[24:27], v0 offset:16384
	v_exp_f32_e32 v51, v106
	v_cvt_pk_bf16_f32 v164, v70, v71
	v_mfma_f32_16x16x32_bf16 v[20:23], v[20:23], v[32:35], 0
	v_cvt_pk_bf16_f32 v165, v72, v69
	v_cvt_pk_bf16_f32 v166, v40, v41
	v_cvt_pk_bf16_f32 v167, v42, v43
	v_mfma_f32_16x16x32_bf16 v[44:47], v[44:47], v[32:35], 0
	v_cvt_pk_bf16_f32 v168, v48, v49
	v_cvt_pk_bf16_f32 v169, v50, v51
	v_mfma_f32_16x16x32_bf16 v[98:101], v[64:67], v[32:35], 0
	v_mfma_f32_16x16x32_bf16 v[116:119], v[60:63], v[32:35], 0
	v_mfma_f32_16x16x32_bf16 v[136:139], v[124:127], v[32:35], 0
	ds_read_b128 v[32:35], v0 offset:18432
	s_waitcnt lgkmcnt(1)
	v_mfma_f32_16x16x32_bf16 v[68:71], v[24:27], v[162:165], v[52:55]
	v_mfma_f32_16x16x32_bf16 v[72:75], v[24:27], v[166:169], v[20:23]
	s_nop 2
	ds_read_b128 v[20:23], v0 offset:20480
	ds_read_b128 v[24:27], v0 offset:22528
	s_waitcnt lgkmcnt(2)
	v_mfma_f32_16x16x32_bf16 v[60:63], v[32:35], v[162:165], v[56:59]
	v_mfma_f32_16x16x32_bf16 v[64:67], v[32:35], v[166:169], v[44:47]
	s_waitcnt lgkmcnt(1)
	v_mfma_f32_16x16x32_bf16 v[52:55], v[20:23], v[162:165], v[76:79]
	v_mfma_f32_16x16x32_bf16 v[56:59], v[20:23], v[166:169], v[36:39]
	s_waitcnt lgkmcnt(0)
	v_mfma_f32_16x16x32_bf16 v[44:47], v[24:27], v[162:165], v[80:83]
	v_mfma_f32_16x16x32_bf16 v[48:51], v[24:27], v[166:169], v[28:31]
	ds_read_b128 v[20:23], v0 offset:24576
	ds_read_b128 v[24:27], v0 offset:26624
	s_waitcnt lgkmcnt(1)
	v_mfma_f32_16x16x32_bf16 v[36:39], v[20:23], v[162:165], v[84:87]
	v_mfma_f32_16x16x32_bf16 v[40:43], v[20:23], v[166:169], v[88:91]
	ds_read_b128 v[20:23], v0 offset:28672
	ds_read_b128 v[76:79], v0 offset:30720
	s_waitcnt lgkmcnt(2)
	v_mfma_f32_16x16x32_bf16 v[32:35], v[24:27], v[162:165], v[94:97]
	v_mfma_f32_16x16x32_bf16 v[28:31], v[24:27], v[166:169], v[98:101]
	s_waitcnt lgkmcnt(1)
	v_mfma_f32_16x16x32_bf16 v[24:27], v[20:23], v[162:165], v[102:105]
	v_mfma_f32_16x16x32_bf16 v[20:23], v[20:23], v[166:169], v[116:119]
	s_nop 2
	v_add_f32_e64 v116, v2, 0
	v_add_f32_e64 v117, v3, 0
	s_waitcnt lgkmcnt(0)
	v_mfma_f32_16x16x32_bf16 v[84:87], v[76:79], v[162:165], v[120:123]
	v_mov_b32_e32 v0, v117
	v_mfma_f32_16x16x32_bf16 v[80:83], v[76:79], v[166:169], v[128:131]
	v_mfma_f32_16x16x32_bf16 v[88:91], v[124:127], v[162:165], v[132:135]
	v_mfma_f32_16x16x32_bf16 v[76:79], v[124:127], v[166:169], v[136:139]
